# nt only on the read-once in-projection columns (q, gates, pooling, V-side); K feature tiles keep the normal cache policy
# baseline (speedup 1.0000x reference)
; DI void phaseA_tile(const Params& p0, int l, int ft, int mt, char* lds) {
;     ...
;     for (int i = 0; i < 16; ++i) {
;       const int idx = tid + NTHREADS * i;
;       const int row = idx >> 5, c = idx & 31;
;       if (c < nch) {
;         const u32x4 val = *(const u32x4*)(lds + row * 512 + ((c ^ (row & 31)) << 4));
;         *(u32x4*)(p.P + (size_t)(m0 + row) * INW + n0 + c * 8) = val;
;       }
;     }
.Lea_full:
	s_lshl_b32 s29, 1, s68
	s_and_b32 s29, s29, 0x104
	s_cbranch_scc1 .Lea_keep
	s_waitcnt lgkmcnt(15)
	global_store_dwordx4 v8, v[50:53], s[2:3] nt
	s_add_u32 s2, s2, 0x16000
	s_addc_u32 s3, s3, 0
	s_waitcnt lgkmcnt(14)
	global_store_dwordx4 v8, v[54:57], s[2:3] nt
	s_add_u32 s2, s2, 0x16000
	s_addc_u32 s3, s3, 0
	s_waitcnt lgkmcnt(13)
	global_store_dwordx4 v8, v[58:61], s[2:3] nt
	s_add_u32 s2, s2, 0x16000
	s_addc_u32 s3, s3, 0
	s_waitcnt lgkmcnt(12)
	global_store_dwordx4 v8, v[62:65], s[2:3] nt
	s_add_u32 s2, s2, 0x16000
	s_addc_u32 s3, s3, 0
	s_waitcnt lgkmcnt(11)
	global_store_dwordx4 v8, v[66:69], s[2:3] nt
	s_add_u32 s2, s2, 0x16000
	s_addc_u32 s3, s3, 0
	s_waitcnt lgkmcnt(10)
	global_store_dwordx4 v8, v[70:73], s[2:3] nt
	s_add_u32 s2, s2, 0x16000
	s_addc_u32 s3, s3, 0
	s_waitcnt lgkmcnt(9)
	global_store_dwordx4 v8, v[74:77], s[2:3] nt
	s_add_u32 s2, s2, 0x16000
	s_addc_u32 s3, s3, 0
	s_waitcnt lgkmcnt(8)
	global_store_dwordx4 v8, v[78:81], s[2:3] nt
	s_add_u32 s2, s2, 0x16000
	s_addc_u32 s3, s3, 0
	s_waitcnt lgkmcnt(7)
	global_store_dwordx4 v8, v[82:85], s[2:3] nt
	s_add_u32 s2, s2, 0x16000
	s_addc_u32 s3, s3, 0
	s_waitcnt lgkmcnt(6)
	global_store_dwordx4 v8, v[86:89], s[2:3] nt
	s_add_u32 s2, s2, 0x16000
	s_addc_u32 s3, s3, 0
	s_waitcnt lgkmcnt(5)
	global_store_dwordx4 v8, v[90:93], s[2:3] nt
	s_add_u32 s2, s2, 0x16000
	s_addc_u32 s3, s3, 0
	s_waitcnt lgkmcnt(4)
	global_store_dwordx4 v8, v[94:97], s[2:3] nt
	s_add_u32 s2, s2, 0x16000
	s_addc_u32 s3, s3, 0
	s_waitcnt lgkmcnt(3)
	global_store_dwordx4 v8, v[98:101], s[2:3] nt
	s_add_u32 s2, s2, 0x16000
	s_addc_u32 s3, s3, 0
	s_waitcnt lgkmcnt(2)
	global_store_dwordx4 v8, v[102:105], s[2:3] nt
	s_add_u32 s2, s2, 0x16000
	s_addc_u32 s3, s3, 0
	s_waitcnt lgkmcnt(1)
	global_store_dwordx4 v8, v[106:109], s[2:3] nt
	s_add_u32 s2, s2, 0x16000
	s_addc_u32 s3, s3, 0
	s_waitcnt lgkmcnt(0)
	global_store_dwordx4 v8, v[110:113], s[2:3] nt
	s_branch .Lea_stored
.Lea_keep:
	s_waitcnt lgkmcnt(15)
	global_store_dwordx4 v8, v[50:53], s[2:3]
	s_add_u32 s2, s2, 0x16000
	s_addc_u32 s3, s3, 0
	s_waitcnt lgkmcnt(14)
	global_store_dwordx4 v8, v[54:57], s[2:3]
	s_add_u32 s2, s2, 0x16000
	s_addc_u32 s3, s3, 0
	s_waitcnt lgkmcnt(13)
	global_store_dwordx4 v8, v[58:61], s[2:3]
	s_add_u32 s2, s2, 0x16000
	s_addc_u32 s3, s3, 0
	s_waitcnt lgkmcnt(12)
	global_store_dwordx4 v8, v[62:65], s[2:3]
	s_add_u32 s2, s2, 0x16000
	s_addc_u32 s3, s3, 0
	s_waitcnt lgkmcnt(11)
	global_store_dwordx4 v8, v[66:69], s[2:3]
	s_add_u32 s2, s2, 0x16000
	s_addc_u32 s3, s3, 0
	s_waitcnt lgkmcnt(10)
	global_store_dwordx4 v8, v[70:73], s[2:3]
	s_add_u32 s2, s2, 0x16000
	s_addc_u32 s3, s3, 0
	s_waitcnt lgkmcnt(9)
	global_store_dwordx4 v8, v[74:77], s[2:3]
	s_add_u32 s2, s2, 0x16000
	s_addc_u32 s3, s3, 0
	s_waitcnt lgkmcnt(8)
	global_store_dwordx4 v8, v[78:81], s[2:3]
	s_add_u32 s2, s2, 0x16000
	s_addc_u32 s3, s3, 0
	s_waitcnt lgkmcnt(7)
	global_store_dwordx4 v8, v[82:85], s[2:3]
	s_add_u32 s2, s2, 0x16000
	s_addc_u32 s3, s3, 0
	s_waitcnt lgkmcnt(6)
	global_store_dwordx4 v8, v[86:89], s[2:3]
	s_add_u32 s2, s2, 0x16000
	s_addc_u32 s3, s3, 0
	s_waitcnt lgkmcnt(5)
	global_store_dwordx4 v8, v[90:93], s[2:3]
	s_add_u32 s2, s2, 0x16000
	s_addc_u32 s3, s3, 0
	s_waitcnt lgkmcnt(4)
	global_store_dwordx4 v8, v[94:97], s[2:3]
	s_add_u32 s2, s2, 0x16000
	s_addc_u32 s3, s3, 0
	s_waitcnt lgkmcnt(3)
	global_store_dwordx4 v8, v[98:101], s[2:3]
	s_add_u32 s2, s2, 0x16000
	s_addc_u32 s3, s3, 0
	s_waitcnt lgkmcnt(2)
	global_store_dwordx4 v8, v[102:105], s[2:3]
	s_add_u32 s2, s2, 0x16000
	s_addc_u32 s3, s3, 0
	s_waitcnt lgkmcnt(1)
	global_store_dwordx4 v8, v[106:109], s[2:3]
	s_add_u32 s2, s2, 0x16000
	s_addc_u32 s3, s3, 0
	s_waitcnt lgkmcnt(0)
	global_store_dwordx4 v8, v[110:113], s[2:3]
.Lea_stored:
	s_mov_b64 exec, -1
